# S5 gate-residual GEMM epilogue pipelined across the two wave rows (three hand-over barriers)
# baseline (speedup 1.0000x reference)
; #define PG8_STAGE(bufoff, gbase, voff) do { _Pragma("unroll") for (int _i = 0; _i < 2; ++_i) \
;         __builtin_amdgcn_global_load_lds((const unsigned*)((const char*)(gbase) + (voff)[_i]), (LAS unsigned*)(lds + (bufoff) + ldsw + _i * 8192), 16, 0, 0); } while (0)
; #define PG8_LDA(dst, b, h) do { _Pragma("unroll") for (int m = 0; m < 4; ++m) _Pragma("unroll") for (int k = 0; k < 2; ++k) dst[m][k] = *(const LAS bf16x8*)(lds + PG8_SA(b, h) + aoff + m * 2048 + k * 1024); } while (0)
; #define PG8_LDB(dst, b, h) do { _Pragma("unroll") for (int n = 0; n < 2; ++n) _Pragma("unroll") for (int k = 0; k < 2; ++k) dst[n][k] = *(const LAS bf16x8*)(lds + PG8_SB(b, h) + boff + n * 2048 + k * 1024); } while (0)
; #define PG8_MMA(ai, bj, At, Bt) do { __builtin_amdgcn_s_setprio(1); _Pragma("unroll") for (int m = 0; m < 4; ++m) _Pragma("unroll") for (int n = 0; n < 2; ++n) _Pragma("unroll") for (int k = 0; k < 2; ++k) \
;         acc[ai][bj][m][n] = __builtin_amdgcn_mfma_f32_16x16x32_bf16(Bt[n][k], At[m][k], acc[ai][bj][m][n], 0, 0, 0); __builtin_amdgcn_s_setprio(0); } while (0)
; #define PG8_WAIT_V(n) asm volatile("s_waitcnt vmcnt(" #n ")" ::: "memory")
; #define PG8_WAIT_L(n) asm volatile("s_waitcnt lgkmcnt(" #n ")" ::: "memory")
; template <class Epi>
; __device__ __forceinline__ void gemm_phase(LAS unsigned char* lds, const Gemm g, const StaticOrder& S, const Epi& E) {
;     ...
;         for (int t = 0; t < nt; t += 2) {
;             const bool last = (t == nt - 2);
;             const char* a1 = cA + (size_t)(t + 1) * kstep;
;             const char* a2 = last ? nA : cA + (size_t)(t + 2) * kstep; const char* b2 = last ? nB : cB + (size_t)(t + 2) * kstep;
;             const char* a3 = a2 + kstep; const char* b3 = b2 + kstep;
;             PG8_LDB(B0, 0, 0); PG8_SCHED; PG8_LDA(At, 0, 0); PG8_STAGE(PG8_SA(1, 1), a1 + hstepA, voffA);
;             PG8_WAIT_L(8); PG8_BAR; PG8_WAIT_L(0); PG8_MMA(0, 0, At, B0); PG8_BAR; PG8_SCHED;
;             PG8_LDB(B1, 0, 1); PG8_STAGE(PG8_SB(0, 0), b2, voffB);
;             PG8_BAR; PG8_WAIT_L(0); PG8_MMA(0, 1, At, B1); PG8_BAR;
;             PG8_LDA(At, 0, 1); PG8_STAGE(PG8_SA(0, 0), a2, voffA);
;             PG8_BAR; PG8_WAIT_L(0); PG8_MMA(1, 0, At, B0); PG8_BAR; PG8_SCHED;
;             PG8_STAGE(PG8_SB(0, 1), b2 + hstepB, voffB);
;             PG8_WAIT_V(6); PG8_BAR; PG8_MMA(1, 1, At, B1); PG8_BAR;
.LBB0_638:
	ds_read_b128 v[128:131], v185
	ds_read_b128 v[132:135], v185 offset:1024
	ds_read_b128 v[136:139], v185 offset:2048
	ds_read_b128 v[140:143], v185 offset:3072
	s_add_u32 s42, s40, 0xfffc0080
	s_addc_u32 s43, s41, -1
	s_cmp_eq_u32 s76, 12
	s_cselect_b32 s45, s31, s43
	s_cselect_b32 s44, s72, s42
	s_cselect_b32 s43, s29, s75
	s_cselect_b32 s42, s73, s74
	v_lshl_add_u64 v[180:181], s[40:41], 0, v[164:165]
	s_add_i32 m0, s39, 0xc000
	ds_read_b128 v[144:147], v186
	ds_read_b128 v[148:151], v186 offset:1024
	ds_read_b128 v[152:155], v186 offset:2048
	ds_read_b128 v[172:175], v186 offset:3072
	ds_read_b128 v[176:179], v186 offset:4096
	ds_read_b128 v[188:191], v186 offset:5120
	ds_read_b128 v[192:195], v186 offset:6144
	ds_read_b128 v[196:199], v186 offset:7168
	global_load_lds_dwordx4 v[180:181], off
	v_lshl_add_u64 v[180:181], s[40:41], 0, v[166:167]
	s_add_i32 m0, s39, 0xe000
	s_nop 0
	global_load_lds_dwordx4 v[180:181], off
	ds_read_b128 v[200:203], v187
	ds_read_b128 v[204:207], v187 offset:1024
	ds_read_b128 v[208:211], v187 offset:2048
	ds_read_b128 v[212:215], v187 offset:3072
	s_waitcnt lgkmcnt(0)
	s_barrier
	s_setprio 1
	v_mfma_f32_16x16x32_bf16 v[124:127], v[128:131], v[144:147], v[124:127]
	v_mfma_f32_16x16x32_bf16 v[116:119], v[136:139], v[144:147], v[116:119]
	v_mfma_f32_16x16x32_bf16 v[108:111], v[128:131], v[152:155], v[108:111]
	v_mfma_f32_16x16x32_bf16 v[100:103], v[136:139], v[152:155], v[100:103]
	v_mfma_f32_16x16x32_bf16 v[92:95], v[128:131], v[176:179], v[92:95]
	v_mfma_f32_16x16x32_bf16 v[84:87], v[136:139], v[176:179], v[84:87]
	v_mfma_f32_16x16x32_bf16 v[76:79], v[128:131], v[192:195], v[76:79]
	v_mfma_f32_16x16x32_bf16 v[68:71], v[136:139], v[192:195], v[68:71]
	v_mfma_f32_16x16x32_bf16 v[124:127], v[132:135], v[148:151], v[124:127]
	v_mfma_f32_16x16x32_bf16 v[116:119], v[140:143], v[148:151], v[116:119]
	v_mfma_f32_16x16x32_bf16 v[108:111], v[132:135], v[172:175], v[108:111]
	v_mfma_f32_16x16x32_bf16 v[100:103], v[140:143], v[172:175], v[100:103]
	v_mfma_f32_16x16x32_bf16 v[92:95], v[132:135], v[188:191], v[92:95]
	v_mfma_f32_16x16x32_bf16 v[84:87], v[140:143], v[188:191], v[84:87]
	v_mfma_f32_16x16x32_bf16 v[76:79], v[132:135], v[196:199], v[76:79]
	v_mfma_f32_16x16x32_bf16 v[68:71], v[140:143], v[196:199], v[68:71]
	v_mfma_f32_16x16x32_bf16 v[120:123], v[200:203], v[144:147], v[120:123]
	v_mfma_f32_16x16x32_bf16 v[112:115], v[208:211], v[144:147], v[112:115]
	v_mfma_f32_16x16x32_bf16 v[104:107], v[200:203], v[152:155], v[104:107]
	v_mfma_f32_16x16x32_bf16 v[96:99], v[208:211], v[152:155], v[96:99]
	v_mfma_f32_16x16x32_bf16 v[88:91], v[200:203], v[176:179], v[88:91]
	v_mfma_f32_16x16x32_bf16 v[80:83], v[208:211], v[176:179], v[80:83]
	v_mfma_f32_16x16x32_bf16 v[72:75], v[200:203], v[192:195], v[72:75]
	v_mfma_f32_16x16x32_bf16 v[64:67], v[208:211], v[192:195], v[64:67]
	v_mfma_f32_16x16x32_bf16 v[120:123], v[204:207], v[148:151], v[120:123]
	v_mfma_f32_16x16x32_bf16 v[112:115], v[212:215], v[148:151], v[112:115]
	v_mfma_f32_16x16x32_bf16 v[104:107], v[204:207], v[172:175], v[104:107]
	v_mfma_f32_16x16x32_bf16 v[96:99], v[212:215], v[172:175], v[96:99]
	v_mfma_f32_16x16x32_bf16 v[88:91], v[204:207], v[188:191], v[88:91]
	v_mfma_f32_16x16x32_bf16 v[80:83], v[212:215], v[188:191], v[80:83]
	v_mfma_f32_16x16x32_bf16 v[72:75], v[204:207], v[196:199], v[72:75]
	v_mfma_f32_16x16x32_bf16 v[64:67], v[212:215], v[196:199], v[64:67]
	s_setprio 0
	s_barrier
	s_nop 1
	ds_read_b128 v[144:147], v186 offset:16384
	ds_read_b128 v[148:151], v186 offset:17408
	ds_read_b128 v[152:155], v186 offset:18432
	ds_read_b128 v[172:175], v186 offset:19456
	ds_read_b128 v[176:179], v186 offset:20480
	ds_read_b128 v[188:191], v186 offset:21504
	ds_read_b128 v[192:195], v186 offset:22528
	ds_read_b128 v[196:199], v186 offset:23552
	s_add_i32 s77, s69, s7
	v_lshl_add_u64 v[180:181], s[42:43], 0, v[158:159]
	s_mov_b32 m0, s77
	s_nop 0
	global_load_lds_dwordx4 v[180:181], off
	v_lshl_add_u64 v[216:217], s[42:43], 0, v[162:163]
	s_add_i32 m0, s77, 0x2000
	s_nop 0
	global_load_lds_dwordx4 v[216:217], off
	s_mov_b32 m0, s39
	v_lshl_add_u64 v[220:221], s[44:45], 0, v[156:157]
	global_load_lds_dwordx4 v[220:221], off
	v_lshl_add_u64 v[222:223], s[44:45], 0, v[160:161]
	s_mov_b32 m0, s46
	s_nop 0
	global_load_lds_dwordx4 v[222:223], off
	s_add_u32 s78, s42, 0x40000
	s_addc_u32 s79, s43, 0
	s_add_i32 s77, s70, s7
	v_lshl_add_u64 v[254:255], s[78:79], 0, v[158:159]
	s_mov_b32 m0, s77
	s_nop 0
	global_load_lds_dwordx4 v[254:255], off
	v_lshl_add_u64 v[254:255], s[78:79], 0, v[162:163]
	s_add_i32 m0, s77, 0x2000
	s_nop 0
	global_load_lds_dwordx4 v[254:255], off
	s_waitcnt vmcnt(6)
	s_waitcnt lgkmcnt(0)
	s_barrier
; #define PG8_STAGE(bufoff, gbase, voff) do { _Pragma("unroll") for (int _i = 0; _i < 2; ++_i) \
;         __builtin_amdgcn_global_load_lds((const unsigned*)((const char*)(gbase) + (voff)[_i]), (LAS unsigned*)(lds + (bufoff) + ldsw + _i * 8192), 16, 0, 0); } while (0)
; #define PG8_LDA(dst, b, h) do { _Pragma("unroll") for (int m = 0; m < 4; ++m) _Pragma("unroll") for (int k = 0; k < 2; ++k) dst[m][k] = *(const LAS bf16x8*)(lds + PG8_SA(b, h) + aoff + m * 2048 + k * 1024); } while (0)
; #define PG8_LDB(dst, b, h) do { _Pragma("unroll") for (int n = 0; n < 2; ++n) _Pragma("unroll") for (int k = 0; k < 2; ++k) dst[n][k] = *(const LAS bf16x8*)(lds + PG8_SB(b, h) + boff + n * 2048 + k * 1024); } while (0)
; #define PG8_MMA(ai, bj, At, Bt) do { __builtin_amdgcn_s_setprio(1); _Pragma("unroll") for (int m = 0; m < 4; ++m) _Pragma("unroll") for (int n = 0; n < 2; ++n) _Pragma("unroll") for (int k = 0; k < 2; ++k) \
;         acc[ai][bj][m][n] = __builtin_amdgcn_mfma_f32_16x16x32_bf16(Bt[n][k], At[m][k], acc[ai][bj][m][n], 0, 0, 0); __builtin_amdgcn_s_setprio(0); } while (0)
; #define PG8_WAIT_V(n) asm volatile("s_waitcnt vmcnt(" #n ")" ::: "memory")
; #define PG8_WAIT_L(n) asm volatile("s_waitcnt lgkmcnt(" #n ")" ::: "memory")
; #define PG8_BAR __builtin_amdgcn_s_barrier()
; #define PG8_SCHED __builtin_amdgcn_sched_barrier(0)
; template <class Epi>
; __device__ __forceinline__ void gemm_phase(LAS unsigned char* lds, const Gemm g, const StaticOrder& S, const Epi& E) {
;     ...
;             PG8_BAR; PG8_WAIT_L(0); PG8_MMA(1, 0, At, B0); PG8_BAR; PG8_SCHED;
;             PG8_STAGE(PG8_SB(0, 1), b2 + hstepB, voffB);
;             PG8_WAIT_V(6); PG8_BAR; PG8_MMA(1, 1, At, B1); PG8_BAR;
;             PG8_LDB(B0, 1, 0); PG8_SCHED; PG8_LDA(At, 1, 0); PG8_STAGE(PG8_SA(0, 1), a2 + hstepA, voffA);
;             PG8_WAIT_L(8); PG8_BAR; PG8_WAIT_L(0); PG8_MMA(0, 0, At, B0); PG8_BAR; PG8_SCHED;
;             PG8_LDB(B1, 1, 1); PG8_STAGE(PG8_SB(1, 0), b3, voffB);
;             PG8_BAR; PG8_WAIT_L(0); PG8_MMA(0, 1, At, B1); PG8_BAR;
;             PG8_LDA(At, 1, 1); PG8_STAGE(PG8_SA(1, 0), a3, voffA);
;             PG8_BAR; PG8_WAIT_L(0); PG8_MMA(1, 0, At, B0); PG8_BAR; PG8_SCHED;
	s_setprio 1
	v_mfma_f32_16x16x32_bf16 v[60:63], v[128:131], v[144:147], v[60:63]
	v_mfma_f32_16x16x32_bf16 v[52:55], v[136:139], v[144:147], v[52:55]
	v_mfma_f32_16x16x32_bf16 v[44:47], v[128:131], v[152:155], v[44:47]
	v_mfma_f32_16x16x32_bf16 v[36:39], v[136:139], v[152:155], v[36:39]
	v_mfma_f32_16x16x32_bf16 v[28:31], v[128:131], v[176:179], v[28:31]
	v_mfma_f32_16x16x32_bf16 v[20:23], v[136:139], v[176:179], v[20:23]
	v_mfma_f32_16x16x32_bf16 v[12:15], v[128:131], v[192:195], v[12:15]
	v_mfma_f32_16x16x32_bf16 v[4:7], v[136:139], v[192:195], v[4:7]
	v_mfma_f32_16x16x32_bf16 v[60:63], v[132:135], v[148:151], v[60:63]
	v_mfma_f32_16x16x32_bf16 v[52:55], v[140:143], v[148:151], v[52:55]
	v_mfma_f32_16x16x32_bf16 v[44:47], v[132:135], v[172:175], v[44:47]
	v_mfma_f32_16x16x32_bf16 v[36:39], v[140:143], v[172:175], v[36:39]
	v_mfma_f32_16x16x32_bf16 v[28:31], v[132:135], v[188:191], v[28:31]
	v_mfma_f32_16x16x32_bf16 v[20:23], v[140:143], v[188:191], v[20:23]
	v_mfma_f32_16x16x32_bf16 v[12:15], v[132:135], v[196:199], v[12:15]
	v_mfma_f32_16x16x32_bf16 v[4:7], v[140:143], v[196:199], v[4:7]
	v_mfma_f32_16x16x32_bf16 v[56:59], v[200:203], v[144:147], v[56:59]
	v_mfma_f32_16x16x32_bf16 v[48:51], v[208:211], v[144:147], v[48:51]
	v_mfma_f32_16x16x32_bf16 v[40:43], v[200:203], v[152:155], v[40:43]
	v_mfma_f32_16x16x32_bf16 v[32:35], v[208:211], v[152:155], v[32:35]
	v_mfma_f32_16x16x32_bf16 v[24:27], v[200:203], v[176:179], v[24:27]
	v_mfma_f32_16x16x32_bf16 v[16:19], v[208:211], v[176:179], v[16:19]
	v_mfma_f32_16x16x32_bf16 v[8:11], v[200:203], v[192:195], v[8:11]
	v_mfma_f32_16x16x32_bf16 v[0:3], v[208:211], v[192:195], v[0:3]
	v_mfma_f32_16x16x32_bf16 v[56:59], v[204:207], v[148:151], v[56:59]
	v_mfma_f32_16x16x32_bf16 v[48:51], v[212:215], v[148:151], v[48:51]
	v_mfma_f32_16x16x32_bf16 v[40:43], v[204:207], v[172:175], v[40:43]
	v_mfma_f32_16x16x32_bf16 v[32:35], v[212:215], v[172:175], v[32:35]
	v_mfma_f32_16x16x32_bf16 v[24:27], v[204:207], v[188:191], v[24:27]
	v_mfma_f32_16x16x32_bf16 v[16:19], v[212:215], v[188:191], v[16:19]
	v_mfma_f32_16x16x32_bf16 v[8:11], v[204:207], v[196:199], v[8:11]
	v_mfma_f32_16x16x32_bf16 v[0:3], v[212:215], v[196:199], v[0:3]
	s_setprio 0
	s_add_i32 s77, 0, 0x18000
	v_add_u32_e32 v140, s77, v183
	s_barrier
	ds_read_b128 v[128:131], v140
	ds_read_b128 v[132:135], v140 offset:1024
	ds_read_b128 v[136:139], v140 offset:2048
	ds_read_b128 v[140:143], v140 offset:3072
	s_add_u32 s44, s44, 0x40000
	s_addc_u32 s45, s45, 0
	s_mov_b32 m0, s47
	v_lshl_add_u64 v[200:201], s[44:45], 0, v[156:157]
	ds_read_b128 v[144:147], v186 offset:32768
	ds_read_b128 v[148:151], v186 offset:33792
	ds_read_b128 v[152:155], v186 offset:34816
	ds_read_b128 v[172:175], v186 offset:35840
	ds_read_b128 v[176:179], v186 offset:36864
	ds_read_b128 v[188:191], v186 offset:37888
	ds_read_b128 v[192:195], v186 offset:38912
	ds_read_b128 v[196:199], v186 offset:39936
	global_load_lds_dwordx4 v[200:201], off
	v_lshl_add_u64 v[200:201], s[44:45], 0, v[160:161]
	s_mov_b32 m0, s48
	s_nop 0
	global_load_lds_dwordx4 v[200:201], off
	s_add_i32 s44, 0, 0x1c000
	v_add_u32_e32 v212, s44, v183
	ds_read_b128 v[200:203], v212
	ds_read_b128 v[204:207], v212 offset:1024
	ds_read_b128 v[208:211], v212 offset:2048
	ds_read_b128 v[212:215], v212 offset:3072
	s_waitcnt lgkmcnt(0)
	s_barrier
	s_setprio 1
	v_mfma_f32_16x16x32_bf16 v[124:127], v[128:131], v[144:147], v[124:127]
	v_mfma_f32_16x16x32_bf16 v[116:119], v[136:139], v[144:147], v[116:119]
	v_mfma_f32_16x16x32_bf16 v[108:111], v[128:131], v[152:155], v[108:111]
	v_mfma_f32_16x16x32_bf16 v[100:103], v[136:139], v[152:155], v[100:103]
	v_mfma_f32_16x16x32_bf16 v[92:95], v[128:131], v[176:179], v[92:95]
	v_mfma_f32_16x16x32_bf16 v[84:87], v[136:139], v[176:179], v[84:87]
	v_mfma_f32_16x16x32_bf16 v[76:79], v[128:131], v[192:195], v[76:79]
	v_mfma_f32_16x16x32_bf16 v[68:71], v[136:139], v[192:195], v[68:71]
	v_mfma_f32_16x16x32_bf16 v[124:127], v[132:135], v[148:151], v[124:127]
	v_mfma_f32_16x16x32_bf16 v[116:119], v[140:143], v[148:151], v[116:119]
	v_mfma_f32_16x16x32_bf16 v[108:111], v[132:135], v[172:175], v[108:111]
	v_mfma_f32_16x16x32_bf16 v[100:103], v[140:143], v[172:175], v[100:103]
	v_mfma_f32_16x16x32_bf16 v[92:95], v[132:135], v[188:191], v[92:95]
	v_mfma_f32_16x16x32_bf16 v[84:87], v[140:143], v[188:191], v[84:87]
	v_mfma_f32_16x16x32_bf16 v[76:79], v[132:135], v[196:199], v[76:79]
	v_mfma_f32_16x16x32_bf16 v[68:71], v[140:143], v[196:199], v[68:71]
	v_mfma_f32_16x16x32_bf16 v[120:123], v[200:203], v[144:147], v[120:123]
	v_mfma_f32_16x16x32_bf16 v[112:115], v[208:211], v[144:147], v[112:115]
	v_mfma_f32_16x16x32_bf16 v[104:107], v[200:203], v[152:155], v[104:107]
	v_mfma_f32_16x16x32_bf16 v[96:99], v[208:211], v[152:155], v[96:99]
	v_mfma_f32_16x16x32_bf16 v[88:91], v[200:203], v[176:179], v[88:91]
	v_mfma_f32_16x16x32_bf16 v[80:83], v[208:211], v[176:179], v[80:83]
	v_mfma_f32_16x16x32_bf16 v[72:75], v[200:203], v[192:195], v[72:75]
	v_mfma_f32_16x16x32_bf16 v[64:67], v[208:211], v[192:195], v[64:67]
	v_mfma_f32_16x16x32_bf16 v[120:123], v[204:207], v[148:151], v[120:123]
	v_mfma_f32_16x16x32_bf16 v[112:115], v[212:215], v[148:151], v[112:115]
	v_mfma_f32_16x16x32_bf16 v[104:107], v[204:207], v[172:175], v[104:107]
	v_mfma_f32_16x16x32_bf16 v[96:99], v[212:215], v[172:175], v[96:99]
	v_mfma_f32_16x16x32_bf16 v[88:91], v[204:207], v[188:191], v[88:91]
	v_mfma_f32_16x16x32_bf16 v[80:83], v[212:215], v[188:191], v[80:83]
	v_mfma_f32_16x16x32_bf16 v[72:75], v[204:207], v[196:199], v[72:75]
	v_mfma_f32_16x16x32_bf16 v[64:67], v[212:215], v[196:199], v[64:67]
	s_setprio 0
	s_barrier
; #define PG8_STAGE(bufoff, gbase, voff) do { _Pragma("unroll") for (int _i = 0; _i < 2; ++_i) \
;         __builtin_amdgcn_global_load_lds((const unsigned*)((const char*)(gbase) + (voff)[_i]), (LAS unsigned*)(lds + (bufoff) + ldsw + _i * 8192), 16, 0, 0); } while (0)
; #define PG8_MMA(ai, bj, At, Bt) do { __builtin_amdgcn_s_setprio(1); _Pragma("unroll") for (int m = 0; m < 4; ++m) _Pragma("unroll") for (int n = 0; n < 2; ++n) _Pragma("unroll") for (int k = 0; k < 2; ++k) \
;         acc[ai][bj][m][n] = __builtin_amdgcn_mfma_f32_16x16x32_bf16(Bt[n][k], At[m][k], acc[ai][bj][m][n], 0, 0, 0); __builtin_amdgcn_s_setprio(0); } while (0)
; #define PG8_WAIT_V(n) asm volatile("s_waitcnt vmcnt(" #n ")" ::: "memory")
; #define PG8_WAIT_L(n) asm volatile("s_waitcnt lgkmcnt(" #n ")" ::: "memory")
; #define PG8_BAR __builtin_amdgcn_s_barrier()
; #define PG8_SCHED __builtin_amdgcn_sched_barrier(0)
; template <class Epi>
; __device__ __forceinline__ void gemm_phase(LAS unsigned char* lds, const Gemm g, const StaticOrder& S, const Epi& E) {
;     ...
;             PG8_BAR; PG8_WAIT_L(0); PG8_MMA(1, 0, At, B0); PG8_BAR; PG8_SCHED;
;             PG8_STAGE(PG8_SB(1, 1), b3 + hstepB, voffB);
;             PG8_WAIT_V(6); PG8_BAR; PG8_MMA(1, 1, At, B1); PG8_BAR;
;         }
;         E(acc, cur, wr, wc, fr, fq);
;     __device__ __forceinline__ void operator()(AccRef acc, const Unit& u, int wr, int wc, int fr, int fq) const {
;         const int row0 = u.pm * 256 + wr * 64 + fr, col0 = u.pn * 128 + wc * 32 + 8 * fq;
;         f32x4 bv[2], bg[2];
; #pragma unroll
;         for (int n = 0; n < 2; ++n) { bv[n] = *(const f32x4*)(bias + col0 + 4 * n); bg[n] = *(const f32x4*)(bias + D + col0 + 4 * n); }
; #pragma unroll
;         for (int ai = 0; ai < 2; ++ai) {
;             f32x4 xs[4][2];
; #pragma unroll
;             for (int m = 0; m < 4; ++m)
; #pragma unroll
;                 for (int n = 0; n < 2; ++n) xs[m][n] = *(const f32x4*)(x + (size_t)(row0 + ai * 128 + m * 16) * D + col0 + 4 * n);
	s_nop 1
	ds_read_b128 v[144:147], v186 offset:49152
	ds_read_b128 v[148:151], v186 offset:50176
	ds_read_b128 v[152:155], v186 offset:51200
	ds_read_b128 v[172:175], v186 offset:52224
	ds_read_b128 v[176:179], v186 offset:53248
	ds_read_b128 v[188:191], v186 offset:54272
	ds_read_b128 v[192:195], v186 offset:55296
	ds_read_b128 v[196:199], v186 offset:56320
	s_add_i32 s45, s77, s7
	v_lshl_add_u64 v[254:255], v[180:181], 0, s[12:13]
	s_mov_b32 m0, s45
	s_nop 0
	global_load_lds_dwordx4 v[254:255], off
	v_lshl_add_u64 v[254:255], v[216:217], 0, s[12:13]
	s_add_i32 m0, s45, 0x2000
	s_nop 0
	global_load_lds_dwordx4 v[254:255], off
	s_mov_b32 m0, s63
	v_lshl_add_u64 v[254:255], v[220:221], 0, s[12:13]
	global_load_lds_dwordx4 v[254:255], off
	v_lshl_add_u64 v[180:181], v[222:223], 0, s[12:13]
	s_mov_b32 m0, s68
	s_nop 0
	global_load_lds_dwordx4 v[180:181], off
	s_add_u32 s42, s42, 0x40080
	s_addc_u32 s43, s43, 0
	s_add_i32 s44, s44, s7
	v_lshl_add_u64 v[254:255], s[42:43], 0, v[158:159]
	s_mov_b32 m0, s44
	s_nop 0
	global_load_lds_dwordx4 v[254:255], off
	v_lshl_add_u64 v[254:255], s[42:43], 0, v[162:163]
	s_add_i32 m0, s44, 0x2000
	s_nop 0
	global_load_lds_dwordx4 v[254:255], off
	s_waitcnt vmcnt(6)
	s_waitcnt lgkmcnt(0)
	s_barrier
	s_setprio 1
	v_mfma_f32_16x16x32_bf16 v[60:63], v[128:131], v[144:147], v[60:63]
	v_mfma_f32_16x16x32_bf16 v[52:55], v[136:139], v[144:147], v[52:55]
	v_mfma_f32_16x16x32_bf16 v[44:47], v[128:131], v[152:155], v[44:47]
	v_mfma_f32_16x16x32_bf16 v[36:39], v[136:139], v[152:155], v[36:39]
	v_mfma_f32_16x16x32_bf16 v[28:31], v[128:131], v[176:179], v[28:31]
	v_mfma_f32_16x16x32_bf16 v[20:23], v[136:139], v[176:179], v[20:23]
	v_mfma_f32_16x16x32_bf16 v[12:15], v[128:131], v[192:195], v[12:15]
	v_mfma_f32_16x16x32_bf16 v[4:7], v[136:139], v[192:195], v[4:7]
	v_mfma_f32_16x16x32_bf16 v[60:63], v[132:135], v[148:151], v[60:63]
	v_mfma_f32_16x16x32_bf16 v[52:55], v[140:143], v[148:151], v[52:55]
	v_mfma_f32_16x16x32_bf16 v[44:47], v[132:135], v[172:175], v[44:47]
	v_mfma_f32_16x16x32_bf16 v[36:39], v[140:143], v[172:175], v[36:39]
	v_mfma_f32_16x16x32_bf16 v[28:31], v[132:135], v[188:191], v[28:31]
	v_mfma_f32_16x16x32_bf16 v[20:23], v[140:143], v[188:191], v[20:23]
	v_mfma_f32_16x16x32_bf16 v[12:15], v[132:135], v[196:199], v[12:15]
	v_mfma_f32_16x16x32_bf16 v[4:7], v[140:143], v[196:199], v[4:7]
	v_mfma_f32_16x16x32_bf16 v[56:59], v[200:203], v[144:147], v[56:59]
	v_mfma_f32_16x16x32_bf16 v[48:51], v[208:211], v[144:147], v[48:51]
	v_mfma_f32_16x16x32_bf16 v[40:43], v[200:203], v[152:155], v[40:43]
	v_mfma_f32_16x16x32_bf16 v[32:35], v[208:211], v[152:155], v[32:35]
	v_mfma_f32_16x16x32_bf16 v[24:27], v[200:203], v[176:179], v[24:27]
	v_mfma_f32_16x16x32_bf16 v[16:19], v[208:211], v[176:179], v[16:19]
	v_mfma_f32_16x16x32_bf16 v[8:11], v[200:203], v[192:195], v[8:11]
	v_mfma_f32_16x16x32_bf16 v[0:3], v[208:211], v[192:195], v[0:3]
	v_mfma_f32_16x16x32_bf16 v[56:59], v[204:207], v[148:151], v[56:59]
	v_mfma_f32_16x16x32_bf16 v[48:51], v[212:215], v[148:151], v[48:51]
	v_mfma_f32_16x16x32_bf16 v[40:43], v[204:207], v[172:175], v[40:43]
	v_mfma_f32_16x16x32_bf16 v[32:35], v[212:215], v[172:175], v[32:35]
	v_mfma_f32_16x16x32_bf16 v[24:27], v[204:207], v[188:191], v[24:27]
	v_mfma_f32_16x16x32_bf16 v[16:19], v[212:215], v[188:191], v[16:19]
	v_mfma_f32_16x16x32_bf16 v[8:11], v[204:207], v[196:199], v[8:11]
	v_mfma_f32_16x16x32_bf16 v[0:3], v[212:215], v[196:199], v[0:3]
	s_setprio 0
	s_add_i32 s76, s76, 2
	s_add_u32 s40, s40, 0x100
	s_addc_u32 s41, s41, 0
	s_add_u32 s74, s74, 0x100
	s_addc_u32 s75, s75, 0
	s_cmp_gt_u32 s76, 13
	s_barrier
	s_cbranch_scc0 .LBB0_638
	v_lshl_or_b32 v128, s71, 7, v184
	v_ashrrev_i32_e32 v129, 31, v128
	v_lshlrev_b64 v[172:173], 2, v[128:129]
	v_lshl_add_u64 v[128:129], s[14:15], 0, v[172:173]
	global_load_dwordx4 v[140:143], v[128:129], off
	v_lshl_add_u64 v[130:131], s[10:11], 0, v[172:173]
	global_load_dwordx4 v[136:139], v[130:131], off
	global_load_dwordx4 v[132:135], v[128:129], off offset:16
	s_nop 0
	global_load_dwordx4 v[128:131], v[130:131], off offset:16
	v_lshl_add_u32 v144, s38, 8, v182
	v_ashrrev_i32_e32 v145, 31, v144
	v_lshlrev_b64 v[176:177], 12, v[144:145]
	v_lshl_add_u64 v[174:175], s[52:53], 0, v[172:173]
	v_lshl_add_u64 v[146:147], v[174:175], 0, v[176:177]
	global_load_dwordx4 v[188:191], v[146:147], off
	global_load_dwordx4 v[192:195], v[146:147], off offset:16
	v_or_b32_e32 v146, 16, v144
	v_or_b32_e32 v148, 32, v144
	v_or_b32_e32 v144, 48, v144
	v_ashrrev_i32_e32 v147, 31, v146
	v_ashrrev_i32_e32 v149, 31, v148
	v_ashrrev_i32_e32 v145, 31, v144
	v_lshlrev_b64 v[208:209], 12, v[146:147]
	v_lshlrev_b64 v[180:181], 12, v[148:149]
	v_lshlrev_b64 v[178:179], 12, v[144:145]
	v_lshl_add_u64 v[146:147], v[174:175], 0, v[208:209]
	v_lshl_add_u64 v[144:145], s[52:53], 0, v[176:177]
	global_load_dwordx4 v[196:199], v[146:147], off offset:16
	global_load_dwordx4 v[200:203], v[146:147], off
	v_lshl_add_u64 v[146:147], v[174:175], 0, v[180:181]
	v_lshl_add_u64 v[148:149], v[174:175], 0, v[178:179]
	v_lshl_add_u64 v[210:211], v[144:145], 0, v[172:173]
	global_load_dwordx4 v[152:155], v[146:147], off offset:16
	global_load_dwordx4 v[204:207], v[146:147], off
	s_nop 0
	global_load_dwordx4 v[144:147], v[148:149], off offset:16
	s_nop 0
	global_load_dwordx4 v[148:151], v[148:149], off
	s_and_b64 vcc, exec, s[8:9]
	s_mov_b32 s71, s28
	s_mov_b32 s38, s30
	s_mov_b64 s[42:43], s[36:37]
	s_mov_b64 s[40:41], s[34:35]
	s_waitcnt vmcnt(0)
; __device__ __forceinline__ float sigmoidf_(float x) { return __builtin_amdgcn_rcpf(1.0f + __expf(-x)); }
;     __device__ __forceinline__ void operator()(AccRef acc, const Unit& u, int wr, int wc, int fr, int fq) const {
;     ...
;                 for (int n = 0; n < 2; ++n) { f32x4 xv = xs[m][n]; const f32x4 v = acc[ai][0][m][n] + bv[n], gt = acc[ai][1][m][n] + bg[n];
; #pragma unroll
;                     for (int j = 0; j < 4; ++j) xv[j] += v[j] * sigmoidf_(gt[j]);
;                     *(f32x4*)(x + (size_t)(row0 + ai * 128 + m * 16) * D + col0 + 4 * n) = xv; }
	v_pk_add_f32 v[108:109], v[108:109], v[136:137]
	v_add_f32_e32 v212, v120, v140
	v_add_f32_e32 v213, v121, v141
	v_add_f32_e32 v214, v122, v142
	v_add_f32_e32 v215, v123, v143
	v_pk_add_f32 v[120:121], v[126:127], v[138:139]
	v_pk_add_f32 v[122:123], v[124:125], v[136:137]
	v_add_f32_e32 v112, v112, v132
	v_add_f32_e32 v113, v113, v133
	v_add_f32_e32 v104, v104, v140
	v_mul_f32_e32 v124, 0xbfb8aa3b, v212
	v_mul_f32_e32 v125, 0xbfb8aa3b, v213
	v_mul_f32_e32 v126, 0xbfb8aa3b, v214
	v_mul_f32_e32 v127, 0xbfb8aa3b, v215
	v_mul_f32_e32 v112, 0xbfb8aa3b, v112
	v_mul_f32_e32 v113, 0xbfb8aa3b, v113
	v_mul_f32_e32 v104, 0xbfb8aa3b, v104
	v_exp_f32_e32 v124, v124
	v_exp_f32_e32 v125, v125
	v_exp_f32_e32 v126, v126
	v_exp_f32_e32 v127, v127
	v_exp_f32_e32 v112, v112
	v_exp_f32_e32 v113, v113
	v_exp_f32_e32 v104, v104
	v_add_f32_e32 v114, v114, v134
	v_add_f32_e32 v115, v115, v135
	v_add_f32_e32 v105, v105, v141
	v_mul_f32_e32 v114, 0xbfb8aa3b, v114
	v_mul_f32_e32 v115, 0xbfb8aa3b, v115
	v_mul_f32_e32 v105, 0xbfb8aa3b, v105
	v_exp_f32_e32 v114, v114
	v_exp_f32_e32 v115, v115
	v_exp_f32_e32 v213, v105
	v_add_f32_e32 v105, 1.0, v124
	v_add_f32_e32 v124, 1.0, v125
	v_add_f32_e32 v125, 1.0, v126
	v_add_f32_e32 v126, 1.0, v127
	v_add_f32_e32 v127, 1.0, v112
	v_add_f32_e32 v212, 1.0, v113
	v_add_f32_e32 v214, 1.0, v104
	v_rcp_f32_e32 v104, v105
	v_rcp_f32_e32 v105, v124
	v_rcp_f32_e32 v112, v125
	v_rcp_f32_e32 v113, v126
	v_add_f32_e32 v114, 1.0, v114
	v_add_f32_e32 v115, 1.0, v115
	v_add_f32_e32 v106, v106, v142
	v_rcp_f32_e32 v124, v127
	v_rcp_f32_e32 v126, v114
	v_rcp_f32_e32 v127, v115
	v_pk_fma_f32 v[114:115], v[120:121], v[112:113], v[190:191]
	v_pk_fma_f32 v[112:113], v[122:123], v[104:105], v[188:189]
	v_add_f32_e32 v104, v107, v143
	v_add_f32_e32 v88, v88, v140
	v_add_f32_e32 v89, v89, v141
	v_add_f32_e32 v72, v72, v140
	v_add_f32_e32 v73, v73, v141
	v_mul_f32_e32 v106, 0xbfb8aa3b, v106
	v_mul_f32_e32 v104, 0xbfb8aa3b, v104
	v_add_f32_e32 v96, v96, v132
	v_add_f32_e32 v97, v97, v133
	v_add_f32_e32 v98, v98, v134
	v_add_f32_e32 v99, v99, v135
	v_mul_f32_e32 v88, 0xbfb8aa3b, v88
	v_mul_f32_e32 v89, 0xbfb8aa3b, v89
	v_add_f32_e32 v90, v90, v142
	v_add_f32_e32 v91, v91, v143
	v_add_f32_e32 v80, v80, v132
	v_add_f32_e32 v81, v81, v133
	v_add_f32_e32 v82, v82, v134
	v_add_f32_e32 v83, v83, v135
	v_mul_f32_e32 v72, 0xbfb8aa3b, v72
	v_mul_f32_e32 v73, 0xbfb8aa3b, v73
	v_add_f32_e32 v74, v74, v142
	v_add_f32_e32 v75, v75, v143
	v_add_f32_e32 v64, v64, v132
	v_add_f32_e32 v65, v65, v133
	v_add_f32_e32 v66, v66, v134
	v_add_f32_e32 v67, v67, v135
	v_exp_f32_e32 v106, v106
	v_exp_f32_e32 v105, v104
	v_mul_f32_e32 v96, 0xbfb8aa3b, v96
	v_mul_f32_e32 v97, 0xbfb8aa3b, v97
	s_barrier
	v_mul_f32_e32 v98, 0xbfb8aa3b, v98
	v_mul_f32_e32 v99, 0xbfb8aa3b, v99
	v_exp_f32_e32 v88, v88
	v_exp_f32_e32 v89, v89
	v_mul_f32_e32 v90, 0xbfb8aa3b, v90
	v_mul_f32_e32 v91, 0xbfb8aa3b, v91
	v_mul_f32_e32 v80, 0xbfb8aa3b, v80
	v_mul_f32_e32 v81, 0xbfb8aa3b, v81
	v_mul_f32_e32 v82, 0xbfb8aa3b, v82
	v_mul_f32_e32 v83, 0xbfb8aa3b, v83
	v_exp_f32_e32 v72, v72
	v_exp_f32_e32 v73, v73
	v_mul_f32_e32 v74, 0xbfb8aa3b, v74
	v_mul_f32_e32 v75, 0xbfb8aa3b, v75
	v_mul_f32_e32 v64, 0xbfb8aa3b, v64
	v_mul_f32_e32 v65, 0xbfb8aa3b, v65
	v_mul_f32_e32 v66, 0xbfb8aa3b, v66
	v_mul_f32_e32 v67, 0xbfb8aa3b, v67
	v_exp_f32_e32 v96, v96
	v_exp_f32_e32 v97, v97
	v_exp_f32_e32 v98, v98
	v_exp_f32_e32 v99, v99
	v_exp_f32_e32 v90, v90
	v_exp_f32_e32 v91, v91
	v_exp_f32_e32 v80, v80
	v_exp_f32_e32 v81, v81
	v_exp_f32_e32 v82, v82
	v_exp_f32_e32 v83, v83
	v_exp_f32_e32 v74, v74
	v_exp_f32_e32 v75, v75
	v_exp_f32_e32 v64, v64
	v_exp_f32_e32 v65, v65
	v_exp_f32_e32 v66, v66
	v_exp_f32_e32 v67, v67
	v_add_f32_e32 v107, 1.0, v213
	v_add_f32_e32 v104, 1.0, v106
	v_add_f32_e32 v105, 1.0, v105
	v_add_f32_e32 v88, 1.0, v88
	v_add_f32_e32 v89, 1.0, v89
	v_add_f32_e32 v72, 1.0, v72
	v_add_f32_e32 v73, 1.0, v73
	v_rcp_f32_e32 v125, v212
	v_rcp_f32_e32 v212, v214
	v_rcp_f32_e32 v104, v104
	v_rcp_f32_e32 v105, v105
	v_rcp_f32_e32 v213, v107
	v_add_f32_e32 v96, 1.0, v96
	v_add_f32_e32 v97, 1.0, v97
	v_add_f32_e32 v98, 1.0, v98
	v_add_f32_e32 v99, 1.0, v99
	v_rcp_f32_e32 v88, v88
	v_add_f32_e32 v90, 1.0, v90
	v_add_f32_e32 v91, 1.0, v91
	v_rcp_f32_e32 v89, v89
	v_add_f32_e32 v80, 1.0, v80
	v_add_f32_e32 v81, 1.0, v81
	v_add_f32_e32 v82, 1.0, v82
	v_add_f32_e32 v83, 1.0, v83
	v_rcp_f32_e32 v72, v72
	v_add_f32_e32 v74, 1.0, v74
	v_add_f32_e32 v75, 1.0, v75
	v_rcp_f32_e32 v73, v73
	v_add_f32_e32 v64, 1.0, v64
	v_add_f32_e32 v65, 1.0, v65
	v_add_f32_e32 v66, 1.0, v66
	v_add_f32_e32 v67, 1.0, v67
	v_rcp_f32_e32 v96, v96
	v_rcp_f32_e32 v97, v97
	v_rcp_f32_e32 v98, v98
	v_rcp_f32_e32 v99, v99
	v_rcp_f32_e32 v90, v90
	v_rcp_f32_e32 v91, v91
	v_rcp_f32_e32 v80, v80
	v_rcp_f32_e32 v81, v81
	v_rcp_f32_e32 v82, v82
	v_rcp_f32_e32 v83, v83
	v_rcp_f32_e32 v74, v74
	v_rcp_f32_e32 v75, v75
	v_rcp_f32_e32 v64, v64
	v_rcp_f32_e32 v66, v66
	v_rcp_f32_e32 v67, v67
	v_rcp_f32_e32 v65, v65
	v_pk_add_f32 v[106:107], v[110:111], v[138:139]
	v_pk_add_f32 v[92:93], v[92:93], v[136:137]
	v_pk_add_f32 v[76:77], v[76:77], v[136:137]
	v_pk_fma_f32 v[106:107], v[106:107], v[104:105], v[202:203]
	v_pk_fma_f32 v[104:105], v[108:109], v[212:213], v[200:201]
	v_lshl_add_u64 v[108:109], s[52:53], 0, v[208:209]
	v_pk_add_f32 v[102:103], v[102:103], v[130:131]
	v_pk_add_f32 v[100:101], v[100:101], v[128:129]
	v_pk_add_f32 v[94:95], v[94:95], v[138:139]
	v_pk_fma_f32 v[88:89], v[92:93], v[88:89], v[204:205]
	v_lshl_add_u64 v[92:93], s[52:53], 0, v[180:181]
	v_pk_add_f32 v[86:87], v[86:87], v[130:131]
	v_pk_add_f32 v[84:85], v[84:85], v[128:129]
	v_pk_add_f32 v[78:79], v[78:79], v[138:139]
	v_pk_fma_f32 v[72:73], v[76:77], v[72:73], v[148:149]
	v_lshl_add_u64 v[76:77], s[52:53], 0, v[178:179]
	v_pk_add_f32 v[70:71], v[70:71], v[130:131]
	v_pk_add_f32 v[68:69], v[68:69], v[128:129]
	v_pk_add_f32 v[118:119], v[118:119], v[130:131]
	v_pk_add_f32 v[116:117], v[116:117], v[128:129]
	v_lshl_add_u64 v[108:109], v[108:109], 0, v[172:173]
	v_pk_fma_f32 v[98:99], v[102:103], v[98:99], v[198:199]
	v_pk_fma_f32 v[96:97], v[100:101], v[96:97], v[196:197]
	v_pk_fma_f32 v[90:91], v[94:95], v[90:91], v[206:207]
	v_lshl_add_u64 v[92:93], v[92:93], 0, v[172:173]
	v_pk_fma_f32 v[82:83], v[86:87], v[82:83], v[154:155]
	s_barrier
; __device__ __forceinline__ float sigmoidf_(float x) { return __builtin_amdgcn_rcpf(1.0f + __expf(-x)); }
;     __device__ __forceinline__ void operator()(AccRef acc, const Unit& u, int wr, int wc, int fr, int fq) const {
;     ...
;                 for (int n = 0; n < 2; ++n) xs[m][n] = *(const f32x4*)(x + (size_t)(row0 + ai * 128 + m * 16) * D + col0 + 4 * n);
; #pragma unroll
;             for (int m = 0; m < 4; ++m)
; #pragma unroll
;                 for (int n = 0; n < 2; ++n) { f32x4 xv = xs[m][n]; const f32x4 v = acc[ai][0][m][n] + bv[n], gt = acc[ai][1][m][n] + bg[n];
; #pragma unroll
;                     for (int j = 0; j < 4; ++j) xv[j] += v[j] * sigmoidf_(gt[j]);
;                     *(f32x4*)(x + (size_t)(row0 + ai * 128 + m * 16) * D + col0 + 4 * n) = xv; }
;             asm volatile("" ::: "memory"); }
	v_pk_fma_f32 v[80:81], v[84:85], v[80:81], v[152:153]
	v_pk_fma_f32 v[74:75], v[78:79], v[74:75], v[150:151]
	v_lshl_add_u64 v[76:77], v[76:77], 0, v[172:173]
	v_pk_fma_f32 v[66:67], v[70:71], v[66:67], v[146:147]
	v_pk_fma_f32 v[64:65], v[68:69], v[64:65], v[144:145]
	v_pk_fma_f32 v[118:119], v[118:119], v[126:127], v[194:195]
	v_pk_fma_f32 v[116:117], v[116:117], v[124:125], v[192:193]
	global_store_dwordx4 v[210:211], v[112:115], off
	global_store_dwordx4 v[210:211], v[116:119], off offset:16
	global_store_dwordx4 v[108:109], v[104:107], off
	global_store_dwordx4 v[108:109], v[96:99], off offset:16
	global_store_dwordx4 v[92:93], v[88:91], off
	global_store_dwordx4 v[92:93], v[80:83], off offset:16
	global_store_dwordx4 v[76:77], v[72:75], off
	global_store_dwordx4 v[76:77], v[64:67], off offset:16
	v_lshl_add_u64 v[98:99], v[176:177], 0, s[18:19]
	v_lshl_add_u64 v[100:101], v[176:177], 0, s[22:23]
	v_lshl_add_u64 v[64:65], v[174:175], 0, v[98:99]
	global_load_dwordx4 v[78:81], v[64:65], off
	global_load_dwordx4 v[82:85], v[64:65], off offset:16
	v_lshl_add_u64 v[64:65], v[174:175], 0, v[100:101]
	v_lshl_add_u64 v[102:103], v[176:177], 0, s[24:25]
	v_lshl_add_u64 v[76:77], v[176:177], 0, s[26:27]
	global_load_dwordx4 v[86:89], v[64:65], off offset:16
	global_load_dwordx4 v[90:93], v[64:65], off
	v_lshl_add_u64 v[64:65], v[174:175], 0, v[102:103]
	v_lshl_add_u64 v[68:69], v[174:175], 0, v[76:77]
	global_load_dwordx4 v[72:75], v[64:65], off offset:16
	global_load_dwordx4 v[94:97], v[64:65], off
	s_nop 0
	global_load_dwordx4 v[64:67], v[68:69], off offset:16
	s_nop 0
	global_load_dwordx4 v[68:71], v[68:69], off
	v_add_f32_e32 v56, v56, v140
	v_add_f32_e32 v57, v57, v141
	v_add_f32_e32 v40, v40, v140
	v_add_f32_e32 v41, v41, v141
	v_add_f32_e32 v24, v24, v140
	v_add_f32_e32 v25, v25, v141
	v_add_f32_e32 v8, v8, v140
	v_add_f32_e32 v9, v9, v141
	v_mul_f32_e32 v56, 0xbfb8aa3b, v56
	v_mul_f32_e32 v57, 0xbfb8aa3b, v57
	v_add_f32_e32 v58, v58, v142
	v_add_f32_e32 v59, v59, v143
	v_add_f32_e32 v48, v48, v132
	v_add_f32_e32 v49, v49, v133
	v_add_f32_e32 v50, v50, v134
	v_add_f32_e32 v51, v51, v135
	v_mul_f32_e32 v40, 0xbfb8aa3b, v40
	v_mul_f32_e32 v41, 0xbfb8aa3b, v41
	v_add_f32_e32 v42, v42, v142
	v_add_f32_e32 v43, v43, v143
	v_add_f32_e32 v32, v32, v132
	v_add_f32_e32 v33, v33, v133
	v_add_f32_e32 v34, v34, v134
	v_add_f32_e32 v35, v35, v135
	v_mul_f32_e32 v24, 0xbfb8aa3b, v24
	v_mul_f32_e32 v25, 0xbfb8aa3b, v25
	v_add_f32_e32 v26, v26, v142
	v_add_f32_e32 v27, v27, v143
	v_add_f32_e32 v16, v16, v132
	v_add_f32_e32 v17, v17, v133
	v_add_f32_e32 v18, v18, v134
	v_add_f32_e32 v19, v19, v135
	v_mul_f32_e32 v8, 0xbfb8aa3b, v8
	v_mul_f32_e32 v9, 0xbfb8aa3b, v9
	v_add_f32_e32 v10, v10, v142
	v_add_f32_e32 v11, v11, v143
	v_add_f32_e32 v0, v0, v132
	v_add_f32_e32 v1, v1, v133
	v_add_f32_e32 v2, v2, v134
	v_add_f32_e32 v3, v3, v135
	v_exp_f32_e32 v56, v56
	v_exp_f32_e32 v57, v57
	v_mul_f32_e32 v58, 0xbfb8aa3b, v58
	v_mul_f32_e32 v59, 0xbfb8aa3b, v59
	v_mul_f32_e32 v48, 0xbfb8aa3b, v48
	v_mul_f32_e32 v49, 0xbfb8aa3b, v49
	v_mul_f32_e32 v50, 0xbfb8aa3b, v50
	v_mul_f32_e32 v51, 0xbfb8aa3b, v51
	v_exp_f32_e32 v40, v40
	v_exp_f32_e32 v41, v41
	v_mul_f32_e32 v42, 0xbfb8aa3b, v42
	v_mul_f32_e32 v43, 0xbfb8aa3b, v43
	v_mul_f32_e32 v32, 0xbfb8aa3b, v32
	v_mul_f32_e32 v33, 0xbfb8aa3b, v33
	v_mul_f32_e32 v34, 0xbfb8aa3b, v34
	v_mul_f32_e32 v35, 0xbfb8aa3b, v35
	v_exp_f32_e32 v24, v24
	v_exp_f32_e32 v25, v25
	v_mul_f32_e32 v26, 0xbfb8aa3b, v26
	v_mul_f32_e32 v27, 0xbfb8aa3b, v27
	v_mul_f32_e32 v16, 0xbfb8aa3b, v16
	v_mul_f32_e32 v17, 0xbfb8aa3b, v17
	v_mul_f32_e32 v18, 0xbfb8aa3b, v18
	v_mul_f32_e32 v19, 0xbfb8aa3b, v19
	v_exp_f32_e32 v8, v8
	v_exp_f32_e32 v9, v9
	v_mul_f32_e32 v10, 0xbfb8aa3b, v10
	v_mul_f32_e32 v11, 0xbfb8aa3b, v11
	v_mul_f32_e32 v0, 0xbfb8aa3b, v0
	v_mul_f32_e32 v1, 0xbfb8aa3b, v1
	v_mul_f32_e32 v2, 0xbfb8aa3b, v2
	v_mul_f32_e32 v3, 0xbfb8aa3b, v3
	v_exp_f32_e32 v58, v58
	v_exp_f32_e32 v59, v59
	v_exp_f32_e32 v48, v48
	v_exp_f32_e32 v49, v49
	v_exp_f32_e32 v50, v50
	v_exp_f32_e32 v51, v51
	v_exp_f32_e32 v42, v42
	v_exp_f32_e32 v43, v43
	v_exp_f32_e32 v32, v32
	v_exp_f32_e32 v33, v33
	v_exp_f32_e32 v34, v34
	v_exp_f32_e32 v35, v35
	v_exp_f32_e32 v26, v26
	v_exp_f32_e32 v27, v27
	v_exp_f32_e32 v16, v16
	v_exp_f32_e32 v17, v17
	v_exp_f32_e32 v18, v18
	v_exp_f32_e32 v19, v19
	v_exp_f32_e32 v10, v10
	v_exp_f32_e32 v11, v11
	s_barrier
; __device__ __forceinline__ float sigmoidf_(float x) { return __builtin_amdgcn_rcpf(1.0f + __expf(-x)); }
; #define PG8_WAIT_V(n) asm volatile("s_waitcnt vmcnt(" #n ")" ::: "memory")
; #define PG8_BAR __builtin_amdgcn_s_barrier()
; template <class Epi>
; __device__ __forceinline__ void gemm_phase(LAS unsigned char* lds, const Gemm g, const StaticOrder& S, const Epi& E) {
;     ...
;     PG8_WAIT_V(0);
;     if (wr == 0) PG8_BAR;
;     PG8_BAR;
;     __device__ __forceinline__ void operator()(AccRef acc, const Unit& u, int wr, int wc, int fr, int fq) const {
;     ...
;             for (int m = 0; m < 4; ++m)
; #pragma unroll
;                 for (int n = 0; n < 2; ++n) { f32x4 xv = xs[m][n]; const f32x4 v = acc[ai][0][m][n] + bv[n], gt = acc[ai][1][m][n] + bg[n];
; #pragma unroll
;                     for (int j = 0; j < 4; ++j) xv[j] += v[j] * sigmoidf_(gt[j]);
;                     *(f32x4*)(x + (size_t)(row0 + ai * 128 + m * 16) * D + col0 + 4 * n) = xv; }
;             asm volatile("" ::: "memory"); }
	v_exp_f32_e32 v0, v0
	v_exp_f32_e32 v1, v1
	v_exp_f32_e32 v2, v2
	v_exp_f32_e32 v3, v3
	v_add_f32_e32 v56, 1.0, v56
	v_add_f32_e32 v57, 1.0, v57
	v_add_f32_e32 v40, 1.0, v40
	v_add_f32_e32 v41, 1.0, v41
	v_add_f32_e32 v24, 1.0, v24
	v_add_f32_e32 v25, 1.0, v25
	v_add_f32_e32 v8, 1.0, v8
	v_add_f32_e32 v9, 1.0, v9
	v_rcp_f32_e32 v56, v56
	v_rcp_f32_e32 v57, v57
	v_add_f32_e32 v58, 1.0, v58
	v_add_f32_e32 v59, 1.0, v59
	v_add_f32_e32 v48, 1.0, v48
	v_add_f32_e32 v49, 1.0, v49
	v_add_f32_e32 v50, 1.0, v50
	v_add_f32_e32 v51, 1.0, v51
	v_rcp_f32_e32 v40, v40
	v_rcp_f32_e32 v41, v41
	v_add_f32_e32 v42, 1.0, v42
	v_add_f32_e32 v43, 1.0, v43
	v_add_f32_e32 v32, 1.0, v32
	v_add_f32_e32 v33, 1.0, v33
	v_add_f32_e32 v34, 1.0, v34
	v_add_f32_e32 v35, 1.0, v35
	v_rcp_f32_e32 v24, v24
	v_rcp_f32_e32 v25, v25
	v_add_f32_e32 v26, 1.0, v26
	v_add_f32_e32 v27, 1.0, v27
	v_add_f32_e32 v16, 1.0, v16
	v_add_f32_e32 v17, 1.0, v17
	v_add_f32_e32 v18, 1.0, v18
	v_add_f32_e32 v19, 1.0, v19
	v_rcp_f32_e32 v8, v8
	v_rcp_f32_e32 v9, v9
	v_add_f32_e32 v10, 1.0, v10
	v_add_f32_e32 v11, 1.0, v11
	v_add_f32_e32 v0, 1.0, v0
	v_add_f32_e32 v1, 1.0, v1
	v_add_f32_e32 v2, 1.0, v2
	v_add_f32_e32 v3, 1.0, v3
	v_rcp_f32_e32 v58, v58
	v_rcp_f32_e32 v59, v59
	v_rcp_f32_e32 v48, v48
	v_rcp_f32_e32 v49, v49
	v_rcp_f32_e32 v50, v50
	v_rcp_f32_e32 v51, v51
	v_rcp_f32_e32 v42, v42
	v_rcp_f32_e32 v43, v43
	v_rcp_f32_e32 v32, v32
	v_rcp_f32_e32 v33, v33
	v_rcp_f32_e32 v34, v34
	v_rcp_f32_e32 v35, v35
	v_rcp_f32_e32 v26, v26
	v_rcp_f32_e32 v27, v27
	v_rcp_f32_e32 v16, v16
	v_rcp_f32_e32 v17, v17
	v_rcp_f32_e32 v18, v18
	v_rcp_f32_e32 v19, v19
	v_rcp_f32_e32 v10, v10
	v_rcp_f32_e32 v11, v11
	v_rcp_f32_e32 v0, v0
	v_rcp_f32_e32 v1, v1
	v_rcp_f32_e32 v2, v2
	v_rcp_f32_e32 v3, v3
	v_pk_add_f32 v[60:61], v[60:61], v[136:137]
	v_pk_add_f32 v[44:45], v[44:45], v[136:137]
	v_pk_add_f32 v[28:29], v[28:29], v[136:137]
	v_pk_add_f32 v[12:13], v[12:13], v[136:137]
	v_pk_add_f32 v[62:63], v[62:63], v[138:139]
	s_waitcnt vmcnt(0)
	v_pk_fma_f32 v[56:57], v[60:61], v[56:57], v[78:79]
	v_lshl_add_u64 v[60:61], s[52:53], 0, v[98:99]
	v_pk_add_f32 v[54:55], v[54:55], v[130:131]
	v_pk_add_f32 v[52:53], v[52:53], v[128:129]
	v_pk_add_f32 v[46:47], v[46:47], v[138:139]
	v_pk_fma_f32 v[40:41], v[44:45], v[40:41], v[90:91]
	v_lshl_add_u64 v[44:45], s[52:53], 0, v[100:101]
	v_pk_add_f32 v[38:39], v[38:39], v[130:131]
	v_pk_add_f32 v[36:37], v[36:37], v[128:129]
	v_pk_add_f32 v[30:31], v[30:31], v[138:139]
	v_pk_fma_f32 v[24:25], v[28:29], v[24:25], v[94:95]
	v_lshl_add_u64 v[28:29], s[52:53], 0, v[102:103]
	v_pk_add_f32 v[22:23], v[22:23], v[130:131]
	v_pk_add_f32 v[20:21], v[20:21], v[128:129]
	v_pk_add_f32 v[14:15], v[14:15], v[138:139]
	v_pk_fma_f32 v[8:9], v[12:13], v[8:9], v[68:69]
	v_lshl_add_u64 v[12:13], s[52:53], 0, v[76:77]
	v_pk_add_f32 v[6:7], v[6:7], v[130:131]
	v_pk_add_f32 v[4:5], v[4:5], v[128:129]
	v_pk_fma_f32 v[58:59], v[62:63], v[58:59], v[80:81]
	v_lshl_add_u64 v[60:61], v[60:61], 0, v[172:173]
	v_pk_fma_f32 v[48:49], v[52:53], v[48:49], v[82:83]
	v_pk_fma_f32 v[50:51], v[54:55], v[50:51], v[84:85]
	v_pk_fma_f32 v[42:43], v[46:47], v[42:43], v[92:93]
	v_lshl_add_u64 v[44:45], v[44:45], 0, v[172:173]
	v_pk_fma_f32 v[32:33], v[36:37], v[32:33], v[86:87]
	v_pk_fma_f32 v[34:35], v[38:39], v[34:35], v[88:89]
	v_pk_fma_f32 v[26:27], v[30:31], v[26:27], v[96:97]
	v_lshl_add_u64 v[28:29], v[28:29], 0, v[172:173]
	v_pk_fma_f32 v[16:17], v[20:21], v[16:17], v[72:73]
	v_pk_fma_f32 v[18:19], v[22:23], v[18:19], v[74:75]
	v_pk_fma_f32 v[10:11], v[14:15], v[10:11], v[70:71]
	v_lshl_add_u64 v[12:13], v[12:13], 0, v[172:173]
	v_pk_fma_f32 v[0:1], v[4:5], v[0:1], v[64:65]
	v_pk_fma_f32 v[2:3], v[6:7], v[2:3], v[66:67]
	global_store_dwordx4 v[60:61], v[56:59], off
	global_store_dwordx4 v[60:61], v[48:51], off offset:16
	global_store_dwordx4 v[44:45], v[40:43], off
	global_store_dwordx4 v[44:45], v[32:35], off offset:16
	global_store_dwordx4 v[28:29], v[24:27], off
	global_store_dwordx4 v[28:29], v[16:19], off offset:16
	global_store_dwordx4 v[12:13], v[8:11], off
	global_store_dwordx4 v[12:13], v[0:3], off offset:16
	s_cbranch_vccz .LBB0_631
	s_waitcnt vmcnt(0)
	s_cmpk_gt_u32 s4, 0xff
	s_cbranch_scc1 .LBB0_642
	s_barrier
